# NSA importance without LDS float atomics: A/B parts stored to two arrays, summed at top-k read
# speedup vs baseline: 1.0150x; 1.0075x over previous
.LBB0_1929:
	s_or_b64 exec, exec, s[22:23]
	ds_write_b32 v175, v105 offset:8448
	ds_write_b32 v175, v105 offset:9472
	ds_write_b32 v175, v105 offset:10496
	ds_write_b32 v175, v105 offset:11520
	ds_write_b32 v175, v105 offset:12544
	ds_write_b32 v175, v105 offset:13568
	ds_write_b32 v175, v105 offset:14592
	ds_write_b32 v175, v105 offset:15616
	ds_write_b32 v175, v105 offset:16640
	s_lshl_b32 s20, s66, 1
	s_and_b32 s70, s20, -16
	s_sub_i32 s67, 0x1ff0, s70
	v_add_u32_e32 v132, s67, v103
	s_lshl_b32 s20, s66, 12
	s_and_b32 s54, s20, 0x6000
	s_mov_b32 s55, s39
	v_ashrrev_i32_e32 v133, 31, v132
	s_lshl_b32 s20, s66, 3
	v_lshl_add_u64 v[2:3], v[132:133], 0, s[54:55]
	s_and_b32 s55, s20, 8
	v_lshlrev_b64 v[4:5], 11, v[2:3]
	v_or_b32_e32 v6, s55, v102
	v_lshl_add_u64 v[4:5], s[42:43], 0, v[4:5]
	v_lshlrev_b32_e32 v104, 7, v6
	v_mad_u64_u32 v[6:7], s[20:21], v2, s49, v[124:125]
	v_lshl_add_u64 v[4:5], v[4:5], 0, v[104:105]
	v_mad_i32_i24 v7, v3, s49, v7
	s_lshl_b32 s20, s55, 2
	s_mov_b32 s21, s39
	v_lshl_add_u64 v[4:5], v[4:5], 0, v[122:123]
	v_lshl_add_u64 v[2:3], v[6:7], 0, s[20:21]
	global_load_dwordx4 v[66:69], v[4:5], off offset:32
	global_load_dwordx4 v[70:73], v[4:5], off offset:64
	global_load_dwordx4 v[74:77], v[4:5], off offset:96
	v_lshl_add_u64 v[130:131], v[2:3], 0, v[126:127]
	global_load_dwordx4 v[78:81], v[4:5], off
	global_load_dword v133, v[130:131], off
	global_load_dword v104, v[130:131], off offset:128
	s_and_b32 s20, s65, 7
	s_lshl_b32 s38, s20, 16
	s_lshr_b32 s20, s30, 4
	s_add_i32 s20, s20, 63
	s_lshr_b32 s20, s20, 6
	s_sub_i32 s28, 0, s20
	s_lshr_b32 s20, s67, 4
	s_and_b32 s71, s66, 7
	s_add_i32 s20, s20, 63
	s_lshr_b32 s29, s20, 6
	s_lshl_b32 s30, s71, 16
	s_add_u32 s22, s26, s30
	s_addc_u32 s23, s27, 0
	s_cmpk_lg_i32 s70, 0x1ff0
	s_cselect_b64 s[24:25], -1, 0
	s_cmpk_eq_i32 s70, 0x1ff0
	v_mov_b32_e32 v54, 0
	s_cbranch_scc1 .LBB0_1942
	v_mov_b32_e32 v129, v105
	v_lshl_add_u64 v[2:3], s[22:23], 0, v[128:129]
	v_lshl_add_u64 v[4:5], v[2:3], 0, v[106:107]
	v_lshl_add_u64 v[6:7], v[2:3], 0, v[108:109]
	global_load_dwordx4 v[34:37], v[4:5], off
	global_load_dwordx4 v[38:41], v[6:7], off
	s_cmp_eq_u32 s29, 1
	s_waitcnt vmcnt(1)
	ds_write_b128 v153, v[34:37]
	s_waitcnt vmcnt(0)
	ds_write_b128 v155, v[38:41]
	s_cbranch_scc1 .LBB0_1932
	v_lshl_add_u64 v[2:3], v[2:3], 0, s[40:41]
	v_lshl_add_u64 v[4:5], v[2:3], 0, v[106:107]
	v_lshl_add_u64 v[2:3], v[2:3], 0, v[108:109]
	global_load_dwordx4 v[34:37], v[4:5], off
	global_load_dwordx4 v[38:41], v[2:3], off

.LBB0_1955:
	v_exp_f32_e32 v42, v138
	v_exp_f32_e32 v43, v141
	v_exp_f32_e32 v44, v139
	v_exp_f32_e32 v45, v140
	v_mul_f32_e32 v46, v146, v43
	v_add_f32_e32 v47, v42, v44
	v_add_f32_e32 v47, v45, v47
	v_mul_f32_e32 v48, 0.5, v46
	v_fma_f32 v47, v146, v47, v48
	s_nop 1
	v_add_f32_dpp v48, v48, v48 quad_perm:[1,0,3,2] row_mask:0xf bank_mask:0xf
	v_add_f32_dpp v47, v47, v47 quad_perm:[1,0,3,2] row_mask:0xf bank_mask:0xf
	s_nop 0
	v_add_f32_dpp v48, v48, v48 quad_perm:[2,3,0,1] row_mask:0xf bank_mask:0xf
	v_add_f32_dpp v47, v47, v47 quad_perm:[2,3,0,1] row_mask:0xf bank_mask:0xf
	s_nop 0
	v_add_f32_dpp v48, v48, v48 row_half_mirror row_mask:0xf bank_mask:0xf
	v_add_f32_dpp v47, v47, v47 row_half_mirror row_mask:0xf bank_mask:0xf
	s_and_saveexec_b64 s[20:21], s[4:5]
	ds_write_b32 v147, v47
	ds_write_b32 v147, v48 offset:8452
	s_or_b64 exec, exec, s[20:21]
	v_exp_f32_e32 v49, v54
	v_exp_f32_e32 v54, v55
	v_exp_f32_e32 v55, v57
	v_exp_f32_e32 v56, v56
	v_exp_f32_e32 v46, v58
	v_add_f32_e32 v48, v49, v54
	v_mul_f32_e32 v57, v146, v55
	v_add_f32_e32 v48, v56, v48
	v_mul_f32_e32 v58, 0.5, v57
	v_exp_f32_e32 v47, v59
	v_fma_f32 v59, v146, v48, v58
	s_nop 1
	v_add_f32_dpp v58, v58, v58 quad_perm:[1,0,3,2] row_mask:0xf bank_mask:0xf
	v_add_f32_dpp v59, v59, v59 quad_perm:[1,0,3,2] row_mask:0xf bank_mask:0xf
	s_nop 0
	v_add_f32_dpp v58, v58, v58 quad_perm:[2,3,0,1] row_mask:0xf bank_mask:0xf
	v_add_f32_dpp v59, v59, v59 quad_perm:[2,3,0,1] row_mask:0xf bank_mask:0xf
	s_nop 0
	v_add_f32_dpp v58, v58, v58 row_half_mirror row_mask:0xf bank_mask:0xf
	v_add_f32_dpp v59, v59, v59 row_half_mirror row_mask:0xf bank_mask:0xf
	s_and_saveexec_b64 s[20:21], s[4:5]
	ds_write_b32 v147, v59 offset:8
	ds_write_b32 v147, v58 offset:8460
	s_or_b64 exec, exec, s[20:21]
	v_exp_f32_e32 v48, v52
	v_exp_f32_e32 v52, v53
	v_exp_f32_e32 v53, v60
	v_exp_f32_e32 v50, v50
	v_exp_f32_e32 v51, v51
	v_exp_f32_e32 v57, v61
	v_mul_f32_e32 v58, v146, v52
	v_add_f32_e32 v59, v46, v47
	v_add_f32_e32 v59, v48, v59
	v_mul_f32_e32 v60, 0.5, v58
	v_fma_f32 v59, v146, v59, v60
	s_nop 1
	v_add_f32_dpp v60, v60, v60 quad_perm:[1,0,3,2] row_mask:0xf bank_mask:0xf
	v_add_f32_dpp v59, v59, v59 quad_perm:[1,0,3,2] row_mask:0xf bank_mask:0xf
	s_nop 0
	v_add_f32_dpp v60, v60, v60 quad_perm:[2,3,0,1] row_mask:0xf bank_mask:0xf
	v_add_f32_dpp v59, v59, v59 quad_perm:[2,3,0,1] row_mask:0xf bank_mask:0xf
	s_nop 0
	v_add_f32_dpp v60, v60, v60 row_half_mirror row_mask:0xf bank_mask:0xf
	v_add_f32_dpp v59, v59, v59 row_half_mirror row_mask:0xf bank_mask:0xf
	s_and_saveexec_b64 s[20:21], s[4:5]
	ds_write_b32 v147, v59 offset:16
	ds_write_b32 v147, v60 offset:8468
	s_or_b64 exec, exec, s[20:21]
	v_mul_f32_e32 v58, v146, v57
	v_add_f32_e32 v59, v50, v51
	v_add_f32_e32 v59, v53, v59
	v_mul_f32_e32 v60, 0.5, v58
	v_fma_f32 v59, v146, v59, v60
	s_nop 1
	v_add_f32_dpp v60, v60, v60 quad_perm:[1,0,3,2] row_mask:0xf bank_mask:0xf
	v_add_f32_dpp v59, v59, v59 quad_perm:[1,0,3,2] row_mask:0xf bank_mask:0xf
	s_nop 0
	v_add_f32_dpp v60, v60, v60 quad_perm:[2,3,0,1] row_mask:0xf bank_mask:0xf
	v_add_f32_dpp v59, v59, v59 quad_perm:[2,3,0,1] row_mask:0xf bank_mask:0xf
	s_nop 0
	v_add_f32_dpp v60, v60, v60 row_half_mirror row_mask:0xf bank_mask:0xf
	v_add_f32_dpp v59, v59, v59 row_half_mirror row_mask:0xf bank_mask:0xf
	s_and_saveexec_b64 s[20:21], s[4:5]
	ds_write_b32 v147, v59 offset:24
	ds_write_b32 v147, v60 offset:8476
	s_or_b64 exec, exec, s[20:21]
	v_exp_f32_e32 v58, v142
	v_exp_f32_e32 v59, v145
	v_exp_f32_e32 v60, v143
	v_exp_f32_e32 v61, v144
	v_mul_f32_e32 v138, v146, v59
	v_add_f32_e32 v139, v58, v60
	v_add_f32_e32 v139, v61, v139
	v_mul_f32_e32 v140, 0.5, v138
	v_fma_f32 v139, v146, v139, v140
	s_nop 1
	v_add_f32_dpp v140, v140, v140 quad_perm:[1,0,3,2] row_mask:0xf bank_mask:0xf
	v_add_f32_dpp v139, v139, v139 quad_perm:[1,0,3,2] row_mask:0xf bank_mask:0xf
	s_nop 0
	v_add_f32_dpp v140, v140, v140 quad_perm:[2,3,0,1] row_mask:0xf bank_mask:0xf
	v_add_f32_dpp v139, v139, v139 quad_perm:[2,3,0,1] row_mask:0xf bank_mask:0xf
	s_nop 0
	v_add_f32_dpp v140, v140, v140 row_half_mirror row_mask:0xf bank_mask:0xf
	v_add_f32_dpp v139, v139, v139 row_half_mirror row_mask:0xf bank_mask:0xf
	s_and_saveexec_b64 s[20:21], s[4:5]
	ds_write_b32 v147, v139 offset:32
	ds_write_b32 v147, v140 offset:8484
	s_or_b64 exec, exec, s[20:21]
	v_exp_f32_e32 v62, v62
	v_exp_f32_e32 v65, v65
	v_exp_f32_e32 v63, v63
	v_exp_f32_e32 v64, v64
	v_mul_f32_e32 v138, v146, v65
	v_add_f32_e32 v139, v62, v63
	v_add_f32_e32 v139, v64, v139
	v_mul_f32_e32 v140, 0.5, v138
	v_fma_f32 v139, v146, v139, v140
	s_nop 1
	v_add_f32_dpp v140, v140, v140 quad_perm:[1,0,3,2] row_mask:0xf bank_mask:0xf
	v_add_f32_dpp v139, v139, v139 quad_perm:[1,0,3,2] row_mask:0xf bank_mask:0xf
	s_nop 0
	v_add_f32_dpp v140, v140, v140 quad_perm:[2,3,0,1] row_mask:0xf bank_mask:0xf
	v_add_f32_dpp v139, v139, v139 quad_perm:[2,3,0,1] row_mask:0xf bank_mask:0xf
	s_nop 0
	v_add_f32_dpp v140, v140, v140 row_half_mirror row_mask:0xf bank_mask:0xf
	v_add_f32_dpp v139, v139, v139 row_half_mirror row_mask:0xf bank_mask:0xf
	s_and_saveexec_b64 s[20:21], s[4:5]
	ds_write_b32 v147, v139 offset:40
	ds_write_b32 v147, v140 offset:8492
	s_or_b64 exec, exec, s[20:21]
	v_exp_f32_e32 v38, v38
	v_exp_f32_e32 v41, v41
	v_exp_f32_e32 v39, v39
	v_exp_f32_e32 v40, v40
	v_mul_f32_e32 v138, v146, v41
	v_add_f32_e32 v139, v38, v39
	v_add_f32_e32 v139, v40, v139
	v_mul_f32_e32 v140, 0.5, v138
	v_fma_f32 v139, v146, v139, v140
	s_nop 1
	v_add_f32_dpp v140, v140, v140 quad_perm:[1,0,3,2] row_mask:0xf bank_mask:0xf
	v_add_f32_dpp v139, v139, v139 quad_perm:[1,0,3,2] row_mask:0xf bank_mask:0xf
	s_nop 0
	v_add_f32_dpp v140, v140, v140 quad_perm:[2,3,0,1] row_mask:0xf bank_mask:0xf
	v_add_f32_dpp v139, v139, v139 quad_perm:[2,3,0,1] row_mask:0xf bank_mask:0xf
	s_nop 0
	v_add_f32_dpp v140, v140, v140 row_half_mirror row_mask:0xf bank_mask:0xf
	v_add_f32_dpp v139, v139, v139 row_half_mirror row_mask:0xf bank_mask:0xf
	s_and_saveexec_b64 s[20:21], s[4:5]
	ds_write_b32 v147, v139 offset:48
	ds_write_b32 v147, v140 offset:8500
	s_or_b64 exec, exec, s[20:21]
	v_exp_f32_e32 v34, v34
	v_exp_f32_e32 v37, v37
	v_exp_f32_e32 v35, v35
	v_exp_f32_e32 v36, v36
	v_mul_f32_e32 v138, v146, v37
	v_add_f32_e32 v139, v34, v35
	v_add_f32_e32 v139, v36, v139
	v_mul_f32_e32 v140, 0.5, v138
	v_fma_f32 v139, v146, v139, v140
	s_nop 1
	v_add_f32_dpp v140, v140, v140 quad_perm:[1,0,3,2] row_mask:0xf bank_mask:0xf
	v_add_f32_dpp v139, v139, v139 quad_perm:[1,0,3,2] row_mask:0xf bank_mask:0xf
	s_nop 0
	v_add_f32_dpp v140, v140, v140 quad_perm:[2,3,0,1] row_mask:0xf bank_mask:0xf
	v_add_f32_dpp v139, v139, v139 quad_perm:[2,3,0,1] row_mask:0xf bank_mask:0xf
	s_nop 0
	v_add_f32_dpp v140, v140, v140 row_half_mirror row_mask:0xf bank_mask:0xf
	v_add_f32_dpp v139, v139, v139 row_half_mirror row_mask:0xf bank_mask:0xf
	s_and_saveexec_b64 s[20:21], s[4:5]
	ds_write_b32 v147, v139 offset:56
	ds_write_b32 v147, v140 offset:8508
	s_or_b64 exec, exec, s[20:21]
	s_branch .LBB0_1946

.LBB0_2117:
	s_or_b64 exec, exec, s[30:31]
	v_cmp_ge_u32_e64 s[20:21], s72, v98
	s_waitcnt vmcnt(1)
	v_mov_b32_e32 v34, 0xf149f2ca
	v_mov_b32_e32 v35, 0xf149f2ca
	s_waitcnt lgkmcnt(0)
	s_barrier
	v_cmp_ge_u32_e64 s[22:23], s72, v99
	s_waitcnt vmcnt(0)
	v_add_u32_e32 v38, 0x11200, v168
	s_add_i32 s83, s72, -1
	v_cmp_eq_u32_e64 s[98:99], 0, v98
	v_cmp_eq_u32_e64 s[100:101], s72, v98
	s_or_b64 s[98:99], s[98:99], s[100:101]
	v_cmp_eq_u32_e64 s[100:101], s83, v98
	s_or_b64 s[98:99], s[98:99], s[100:101]
	v_cmp_eq_u32_e64 s[100:101], s72, v99
	v_cmp_eq_u32_e64 s[86:87], s83, v99
	s_or_b64 s[100:101], s[100:101], s[86:87]
	ds_read_b32 v34, v167 offset:36864
	ds_read_b32 v35, v167 offset:37120
	ds_read_b32 v36, v169 offset:36864
	ds_read_b32 v37, v169 offset:37120
	ds_read_b32 v40, v167 offset:45312
	ds_read_b32 v41, v167 offset:45568
	ds_read_b32 v42, v169 offset:45312
	ds_read_b32 v43, v169 offset:45568
	s_waitcnt lgkmcnt(0)
	v_add_f32_e32 v34, v34, v40
	v_add_f32_e32 v35, v35, v41
	v_add_f32_e32 v36, v36, v42
	v_add_f32_e32 v37, v37, v43
	v_cndmask_b32_e64 v34, v34, v191, s[98:99]
	v_cndmask_b32_e64 v35, v35, v191, s[100:101]
	v_cndmask_b32_e64 v36, v36, v191, s[98:99]
	v_cndmask_b32_e64 v37, v37, v191, s[100:101]
	v_max_i32_e32 v34, 0, v34
	v_max_i32_e32 v35, 0, v35
	v_max_i32_e32 v36, 0, v36
	v_max_i32_e32 v37, 0, v37
	v_cndmask_b32_e64 v34, 0, v34, s[20:21]
	v_cndmask_b32_e64 v35, 0, v35, s[22:23]
	v_cndmask_b32_e64 v36, 0, v36, s[20:21]
	v_cndmask_b32_e64 v37, 0, v37, s[22:23]
	s_mov_b32 s24, 0
	s_mov_b32 s57, 0
	s_mov_b32 s82, 0x40000000
.Ltk_loop0:
	s_or_b32 s25, s24, s82
	s_or_b32 s58, s57, s82
	v_cmp_le_u32_e64 s[28:29], s25, v34
	v_cmp_le_u32_e64 s[30:31], s25, v35
	v_cmp_le_u32_e64 s[78:79], s58, v36
	v_cmp_le_u32_e64 s[80:81], s58, v37
	s_bcnt1_i32_b64 s38, s[28:29]
	s_bcnt1_i32_b64 s56, s[30:31]
	s_bcnt1_i32_b64 s32, s[78:79]
	s_bcnt1_i32_b64 s77, s[80:81]
	s_add_i32 s38, s38, s56
	s_add_i32 s32, s32, s77
	s_cmp_ge_u32 s38, 16
	s_cselect_b32 s24, s25, s24
	s_cmp_ge_u32 s32, 16
	s_cselect_b32 s57, s58, s57
	s_lshr_b32 s82, s82, 1
	s_cmp_lg_u32 s82, 0
	s_cbranch_scc1 .Ltk_loop0
	v_cmp_lt_u32_e64 s[28:29], s24, v34
	v_cmp_lt_u32_e64 s[30:31], s24, v35
	v_cmp_eq_u32_e64 s[78:79], s24, v34
	v_cmp_eq_u32_e64 s[80:81], s24, v35
	s_bcnt1_i32_b64 s38, s[28:29]
	s_bcnt1_i32_b64 s56, s[30:31]
	s_add_i32 s38, s38, s56
	s_sub_i32 s38, 16, s38
	v_mbcnt_lo_u32_b32 v39, s78, 0
	v_mbcnt_hi_u32_b32 v39, s79, v39
	v_cmp_gt_u32_e64 s[86:87], s38, v39
	s_and_b64 s[86:87], s[86:87], s[78:79]
	s_or_b64 s[28:29], s[28:29], s[86:87]
	s_and_b64 s[28:29], s[28:29], s[20:21]
	s_bcnt1_i32_b64 s56, s[78:79]
	s_sub_i32 s38, s38, s56
	s_max_i32 s38, s38, 0
	v_mbcnt_lo_u32_b32 v39, s80, 0
	v_mbcnt_hi_u32_b32 v39, s81, v39
	v_cmp_gt_u32_e64 s[86:87], s38, v39
	s_and_b64 s[86:87], s[86:87], s[80:81]
	s_or_b64 s[30:31], s[30:31], s[86:87]
	s_and_b64 s[30:31], s[30:31], s[22:23]
	v_mov_b32_e32 v40, s28
	v_mov_b32_e32 v41, s29
	v_mov_b32_e32 v42, s30
	v_mov_b32_e32 v43, s31
	s_and_saveexec_b64 s[94:95], s[6:7]
	ds_write_b128 v38, v[40:43]
	s_or_b64 exec, exec, s[94:95]
	v_cmp_lt_u32_e64 s[28:29], s57, v36
	v_cmp_lt_u32_e64 s[30:31], s57, v37
	v_cmp_eq_u32_e64 s[78:79], s57, v36
	v_cmp_eq_u32_e64 s[80:81], s57, v37
	s_bcnt1_i32_b64 s38, s[28:29]
	s_bcnt1_i32_b64 s56, s[30:31]
	s_add_i32 s38, s38, s56
	s_sub_i32 s38, 16, s38
	v_mbcnt_lo_u32_b32 v39, s78, 0
	v_mbcnt_hi_u32_b32 v39, s79, v39
	v_cmp_gt_u32_e64 s[86:87], s38, v39
	s_and_b64 s[86:87], s[86:87], s[78:79]
	s_or_b64 s[28:29], s[28:29], s[86:87]
	s_and_b64 s[28:29], s[28:29], s[20:21]
	s_bcnt1_i32_b64 s56, s[78:79]
	s_sub_i32 s38, s38, s56
	s_max_i32 s38, s38, 0
	v_mbcnt_lo_u32_b32 v39, s80, 0
	v_mbcnt_hi_u32_b32 v39, s81, v39
	v_cmp_gt_u32_e64 s[86:87], s38, v39
	s_and_b64 s[86:87], s[86:87], s[80:81]
	s_or_b64 s[30:31], s[30:31], s[86:87]
	s_and_b64 s[30:31], s[30:31], s[22:23]
	v_mov_b32_e32 v40, s28
	v_mov_b32_e32 v41, s29
	v_mov_b32_e32 v42, s30
	v_mov_b32_e32 v43, s31
	s_and_saveexec_b64 s[94:95], s[6:7]
	ds_write_b128 v192, v[40:43]
	s_or_b64 exec, exec, s[94:95]
	ds_read_b32 v34, v170 offset:36864
	ds_read_b32 v35, v170 offset:37120
	ds_read_b32 v36, v171 offset:36864
	ds_read_b32 v37, v171 offset:37120
	ds_read_b32 v40, v170 offset:45312
	ds_read_b32 v41, v170 offset:45568
	ds_read_b32 v42, v171 offset:45312
	ds_read_b32 v43, v171 offset:45568
	s_waitcnt lgkmcnt(0)
	v_add_f32_e32 v34, v34, v40
	v_add_f32_e32 v35, v35, v41
	v_add_f32_e32 v36, v36, v42
	v_add_f32_e32 v37, v37, v43
	v_cndmask_b32_e64 v34, v34, v191, s[98:99]
	v_cndmask_b32_e64 v35, v35, v191, s[100:101]
	v_cndmask_b32_e64 v36, v36, v191, s[98:99]
	v_cndmask_b32_e64 v37, v37, v191, s[100:101]
	v_max_i32_e32 v34, 0, v34
	v_max_i32_e32 v35, 0, v35
	v_max_i32_e32 v36, 0, v36
	v_max_i32_e32 v37, 0, v37
	v_cndmask_b32_e64 v34, 0, v34, s[20:21]
	v_cndmask_b32_e64 v35, 0, v35, s[22:23]
	v_cndmask_b32_e64 v36, 0, v36, s[20:21]
	v_cndmask_b32_e64 v37, 0, v37, s[22:23]
	s_mov_b32 s24, 0
	s_mov_b32 s57, 0
	s_mov_b32 s82, 0x40000000

	.amdhsa_kernel _Z15yoco_megakernel5KArgsii
		.amdhsa_group_segment_fixed_size 73744
		.amdhsa_private_segment_fixed_size 0
		.amdhsa_kernarg_size 512
		.amdhsa_user_sgpr_count 2
		.amdhsa_user_sgpr_dispatch_ptr 0
		.amdhsa_user_sgpr_queue_ptr 0
		.amdhsa_user_sgpr_kernarg_segment_ptr 1
		.amdhsa_user_sgpr_dispatch_id 0
		.amdhsa_user_sgpr_kernarg_preload_length 0
		.amdhsa_user_sgpr_kernarg_preload_offset 0
		.amdhsa_user_sgpr_private_segment_size 0
		.amdhsa_uses_dynamic_stack 0
		.amdhsa_enable_private_segment 0
		.amdhsa_system_sgpr_workgroup_id_x 1
		.amdhsa_system_sgpr_workgroup_id_y 0
		.amdhsa_system_sgpr_workgroup_id_z 0
		.amdhsa_system_sgpr_workgroup_info 0
		.amdhsa_system_vgpr_workitem_id 2
		.amdhsa_next_free_vgpr 234
		.amdhsa_next_free_sgpr 102
		.amdhsa_accum_offset 236
		.amdhsa_reserve_vcc 1
		.amdhsa_float_round_mode_32 0
		.amdhsa_float_round_mode_16_64 0
		.amdhsa_float_denorm_mode_32 3
		.amdhsa_float_denorm_mode_16_64 3
		.amdhsa_dx10_clamp 1
		.amdhsa_ieee_mode 1
		.amdhsa_fp16_overflow 0
		.amdhsa_tg_split 0
		.amdhsa_exception_fp_ieee_invalid_op 0
		.amdhsa_exception_fp_denorm_src 0
		.amdhsa_exception_fp_ieee_div_zero 0
		.amdhsa_exception_fp_ieee_overflow 0
		.amdhsa_exception_fp_ieee_underflow 0
		.amdhsa_exception_fp_ieee_inexact 0
		.amdhsa_exception_int_div_zero 0
	.end_amdhsa_kernel

amdhsa.kernels:
  - .agpr_count:     0
    .args:
      - .offset:         0
        .size:           248
        .value_kind:     by_value
      - .offset:         248
        .size:           4
        .value_kind:     by_value
      - .offset:         252
        .size:           4
        .value_kind:     by_value
      - .offset:         256
        .size:           4
        .value_kind:     hidden_block_count_x
      - .offset:         260
        .size:           4
        .value_kind:     hidden_block_count_y
      - .offset:         264
        .size:           4
        .value_kind:     hidden_block_count_z
      - .offset:         268
        .size:           2
        .value_kind:     hidden_group_size_x
      - .offset:         270
        .size:           2
        .value_kind:     hidden_group_size_y
      - .offset:         272
        .size:           2
        .value_kind:     hidden_group_size_z
      - .offset:         274
        .size:           2
        .value_kind:     hidden_remainder_x
      - .offset:         276
        .size:           2
        .value_kind:     hidden_remainder_y
      - .offset:         278
        .size:           2
        .value_kind:     hidden_remainder_z
      - .offset:         296
        .size:           8
        .value_kind:     hidden_global_offset_x
      - .offset:         304
        .size:           8
        .value_kind:     hidden_global_offset_y
      - .offset:         312
        .size:           8
        .value_kind:     hidden_global_offset_z
      - .offset:         320
        .size:           2
        .value_kind:     hidden_grid_dims
      - .offset:         344
        .size:           8
        .value_kind:     hidden_multigrid_sync_arg
    .group_segment_fixed_size: 73744
    .kernarg_segment_align: 8
    .kernarg_segment_size: 512
    .language:       OpenCL C
    .language_version:
      - 2
      - 0
    .max_flat_workgroup_size: 256
    .name:           _Z15yoco_megakernel5KArgsii
    .private_segment_fixed_size: 0
    .sgpr_count:     108
    .sgpr_spill_count: 38
    .symbol:         _Z15yoco_megakernel5KArgsii.kd
    .uniform_work_group_size: 1
    .uses_dynamic_stack: false
    .vgpr_count:     234
    .vgpr_spill_count: 0
    .wavefront_size: 64
